# attention loops: packed f32 v_pk_mul/v_pk_add split into scalar pairs beside the MFMAs (bit-identical)
# baseline (speedup 1.0000x reference)
; __device__ __forceinline__ float ex2(float v) { return __builtin_amdgcn_exp2f(v); }
; __device__ __forceinline__ int crow(int r, int hi) { return (r & 3) + 8 * (r >> 2) + 4 * hi; }
; #define MFMA32(a, b, c) __builtin_amdgcn_mfma_f32_32x32x16_bf16((a), (b), (c), 0, 0, 0)
; template <bool diag> __device__ __forceinline__ void tileB_post(BStateL& S, const f32x16& y, const bf16x8 (&vf)[4], int ql, int hi) {
;     f32x16 bt, kk;
; #pragma unroll
;     for (int r = 0; r < 16; ++r) {
;         const float t = ex2(__builtin_amdgcn_fmed3f(y[r], -126.f, 126.f));
;         float k_ = __builtin_amdgcn_rcpf(1.0f + t);
;         float b_ = t * k_;
;         if (diag && !(crow(r, hi) < ql)) { b_ = 0.f; k_ = 1.f; }
;         bt[r] = b_; kk[r] = k_;
;     }
;     float G[4], PG[4], tot[4];
; #pragma unroll
;     for (int u = 0; u < 4; ++u) { G[u] = (kk[4 * u] * kk[4 * u + 1]) * (kk[4 * u + 2] * kk[4 * u + 3]); PG[u] = __shfl_xor(G[u], 32); tot[u] = G[u] * PG[u]; }
;     float A[4];
;     A[3] = S.C; A[2] = A[3] * tot[3]; A[1] = A[2] * tot[2]; A[0] = A[1] * tot[1];
;     const float Cn = A[0] * tot[0];
;     f32x16 w;
; #pragma unroll
;     for (int u = 0; u < 4; ++u) {
;         const float F3 = A[u] * (hi == 0 ? PG[u] : 1.0f), F2 = F3 * kk[4 * u + 3], F1 = F2 * kk[4 * u + 2], F0 = F1 * kk[4 * u + 1];
;         w[4 * u + 3] = bt[4 * u + 3] * F3; w[4 * u + 2] = bt[4 * u + 2] * F2; w[4 * u + 1] = bt[4 * u + 1] * F1; w[4 * u] = bt[4 * u] * F0;
;     }
;     S.C = Cn;
;     const bf16x8 p0 = pack8(w, 0), p1 = pack8(w, 8);
;     S.o0 = MFMA32(vf[0], p0, S.o0); S.o0 = MFMA32(vf[1], p1, S.o0);
;     S.o1 = MFMA32(vf[2], p0, S.o1); S.o1 = MFMA32(vf[3], p1, S.o1);
; __device__ __forceinline__ void attnB_wave(LAS unsigned char* st, const bf16* QKV, bf16* O, float* sso, int b, int h, int qi, int lane) {
;     ...
;         if (SB_EARLY_EXIT && __all(!(S.C >= 0x1p-126f))) break;
.LBB0_278:
	s_nop 10
	v_med3_f32 v16, v16, s9, v217
	v_exp_f32_e32 v36, v16
	v_med3_f32 v16, v17, s9, v217
	v_exp_f32_e32 v37, v16
	v_cmp_lt_i32_e32 vcc, v208, v207
	v_add_f32_e32 v16, 1.0, v36
	v_rcp_f32_e32 v38, v16
	v_med3_f32 v16, v18, s9, v217
	v_exp_f32_e32 v40, v16
	v_med3_f32 v18, v19, s9, v217
	v_exp_f32_e32 v42, v18
	v_med3_f32 v18, v20, s9, v217
	v_exp_f32_e32 v43, v18
	v_add_f32_e32 v16, 1.0, v40
	v_rcp_f32_e32 v44, v16
	v_add_f32_e32 v16, 1.0, v42
	v_rcp_f32_e32 v45, v16
	v_add_f32_e32 v16, 1.0, v43
	v_rcp_f32_e32 v46, v16
	v_med3_f32 v16, v21, s9, v217
	v_exp_f32_e32 v47, v16
	v_med3_f32 v19, v22, s9, v217
	v_exp_f32_e32 v84, v19
	v_med3_f32 v19, v23, s9, v217
	v_exp_f32_e32 v85, v19
	v_add_f32_e32 v18, 1.0, v47
	v_rcp_f32_e32 v86, v18
	v_add_f32_e32 v18, 1.0, v84
	v_rcp_f32_e32 v87, v18
	v_add_f32_e32 v18, 1.0, v85
	v_rcp_f32_e32 v88, v18
	v_med3_f32 v18, v24, s9, v217
	v_exp_f32_e32 v89, v18
	v_med3_f32 v21, v25, s9, v217
	v_exp_f32_e32 v25, v21
	v_med3_f32 v21, v26, s9, v217
	v_exp_f32_e32 v90, v21
	v_add_f32_e32 v19, 1.0, v89
	v_rcp_f32_e32 v91, v19
	v_add_f32_e32 v19, 1.0, v25
	v_rcp_f32_e32 v92, v19
	v_add_f32_e32 v19, 1.0, v90
	v_rcp_f32_e32 v93, v19
	v_med3_f32 v19, v27, s9, v217
	v_exp_f32_e32 v27, v19
	v_med3_f32 v23, v30, s9, v217
	v_exp_f32_e32 v30, v23
	v_med3_f32 v23, v31, s9, v217
	v_add_f32_e32 v21, 1.0, v27
	v_rcp_f32_e32 v96, v21
	v_med3_f32 v21, v28, s9, v217
	v_exp_f32_e32 v28, v21
	v_med3_f32 v21, v29, s9, v217
	v_exp_f32_e32 v97, v21
	v_exp_f32_e32 v31, v23
	v_add_f32_e32 v21, 1.0, v28
	v_rcp_f32_e32 v29, v21
	v_add_f32_e32 v21, 1.0, v97
	v_rcp_f32_e32 v111, v21
	v_add_f32_e32 v21, 1.0, v30
	v_add_f32_e32 v17, 1.0, v37
	v_rcp_f32_e32 v113, v21
	v_add_f32_e32 v21, 1.0, v31
	v_rcp_f32_e32 v39, v17
	v_rcp_f32_e32 v138, v21
	v_cndmask_b32_e64 v17, 1.0, v38, s[40:41]
	v_cndmask_b32_e64 v19, 1.0, v91, s[56:57]
	v_cndmask_b32_e64 v41, 1.0, v39, s[42:43]
	v_cndmask_b32_e64 v94, 1.0, v92, s[58:59]
	v_cndmask_b32_e64 v95, 1.0, v93, s[60:61]
	v_cndmask_b32_e64 v110, 1.0, v96, s[62:63]
	v_cndmask_b32_e64 v21, 1.0, v29, s[64:65]
	v_cndmask_b32_e64 v139, 1.0, v111, s[66:67]
	v_cndmask_b32_e64 v140, 1.0, v113, s[68:69]
	v_cndmask_b32_e64 v141, 1.0, v138, s[70:71]
	v_cndmask_b32_e32 v23, v206, v208, vcc
	v_lshlrev_b32_e32 v112, 2, v23
	v_mul_f32_e32 v24, v17, v41
	v_mul_f32_e32 v17, v19, v94
	v_mul_f32_e32 v19, v95, v110
	v_mul_f32_e32 v21, v21, v139
	v_mul_f32_e32 v23, v140, v141
	v_mul_f32_e32 v17, v17, v19
	v_mul_f32_e32 v21, v21, v23
	ds_bpermute_b32 v19, v112, v17
	ds_bpermute_b32 v23, v112, v21
	v_mul_f32_e32 v25, v25, v92
	v_cndmask_b32_e64 v16, 1.0, v46, s[48:49]
	v_mul_f32_e32 v36, v36, v38
	v_mul_f32_e32 v38, v40, v44
	v_mul_f32_e32 v40, v43, v46
	v_cndmask_b32_e64 v46, 0, v25, s[58:59]
	v_mul_f32_e32 v25, v90, v93
	v_cndmask_b32_e64 v18, 1.0, v86, s[50:51]
	v_cndmask_b32_e64 v20, 1.0, v87, s[52:53]
	v_cndmask_b32_e64 v22, 1.0, v88, s[54:55]
	v_mul_f32_e32 v37, v37, v39
	v_mul_f32_e32 v39, v42, v45
	v_mul_f32_e32 v42, v47, v86
	v_cndmask_b32_e64 v47, 0, v25, s[60:61]
	v_mul_f32_e32 v25, v27, v96
	v_mul_f32_e32 v43, v84, v87
	v_cndmask_b32_e64 v84, 0, v25, s[62:63]
	v_mul_f32_e32 v25, v28, v29
	s_waitcnt lgkmcnt(0)
	v_mul_f32_e32 v16, v16, v18
	v_mul_f32_e32 v17, v17, v19
	v_mul_f32_e32 v28, v20, v22
	v_mul_f32_e32 v29, v21, v23
	v_cndmask_b32_e64 v82, 1.0, v44, s[44:45]
	v_mul_f32_e32 v16, v16, v28
	v_mul_f32_e32 v17, v17, v29
	ds_bpermute_b32 v27, v112, v16
	v_cndmask_b32_e64 v83, 1.0, v45, s[46:47]
	v_cndmask_b32_e64 v21, 0, v25, s[64:65]
	v_mul_f32_e32 v25, v97, v111
	v_mul_f32_e32 v26, v82, v83
	v_cndmask_b32_e64 v28, 0, v25, s[66:67]
	v_mov_b32_e32 v25, v16
	s_waitcnt lgkmcnt(0)
	v_mul_f32_e32 v24, v24, v26
	v_mul_f32_e32 v25, v25, v27
	ds_bpermute_b32 v16, v112, v24
	v_mul_f32_e32 v44, v85, v88
	v_cndmask_b32_e64 v27, 1.0, v27, s[38:39]
	v_cndmask_b32_e64 v44, 0, v44, s[54:55]
	v_cndmask_b32_e64 v36, 0, v36, s[40:41]
	s_waitcnt lgkmcnt(0)
	v_mul_f32_e32 v86, v24, v16
	v_mul_f32_e32 v87, v25, v17
	v_mul_f32_e32 v17, v27, v17
	v_cndmask_b32_e64 v16, 1.0, v16, s[38:39]
	v_mul_f32_e32 v22, v22, v17
	v_mul_f32_e32 v27, v44, v17
	v_cndmask_b32_e64 v17, 1.0, v19, s[38:39]
	v_mul_f32_e32 v16, v16, v87
	v_mul_f32_e32 v17, v17, v29
	v_mul_f32_e32 v24, v83, v16
	v_mul_f32_e32 v19, v110, v17
	v_mul_f32_e32 v83, v84, v17
	v_cndmask_b32_e64 v17, 1.0, v23, s[38:39]
	v_mul_f32_e32 v25, v82, v24
	v_mul_f32_e32 v20, v20, v22
	v_mul_f32_e32 v23, v141, v17
	v_cndmask_b32_e64 v37, 0, v37, s[42:43]
	v_cndmask_b32_e64 v38, 0, v38, s[44:45]
	v_cndmask_b32_e64 v39, 0, v39, s[46:47]
	v_cndmask_b32_e64 v40, 0, v40, s[48:49]
	v_cndmask_b32_e64 v42, 0, v42, s[50:51]
	v_cndmask_b32_e64 v43, 0, v43, s[52:53]
	v_mul_f32_e32 v45, v89, v91
	v_mul_f32_e32 v26, v30, v113
	v_mul_f32_e32 v30, v31, v138
	v_mul_f32_e32 v31, v41, v25
	v_mul_f32_e32 v18, v18, v20
	v_mul_f32_e32 v29, v95, v19
	v_mul_f32_e32 v82, v140, v23
	v_cndmask_b32_e64 v45, 0, v45, s[56:57]
	v_cndmask_b32_e64 v26, 0, v26, s[68:69]
	v_cndmask_b32_e64 v30, 0, v30, s[70:71]
	v_mul_f32_e32 v39, v39, v16
	v_mul_f32_e32 v24, v38, v24
	v_mul_f32_e32 v16, v37, v25
	v_mul_f32_e32 v25, v36, v31
	v_mul_f32_e32 v22, v43, v22
	v_mul_f32_e32 v20, v42, v20
	v_mul_f32_e32 v18, v40, v18
	v_mul_f32_e32 v31, v94, v29
	v_mul_f32_e32 v85, v139, v82
	v_mul_f32_e32 v84, v47, v19
	v_mul_f32_e32 v29, v46, v29
	v_mul_f32_e32 v31, v45, v31
	v_mul_f32_e32 v30, v30, v17
	v_cvt_pk_bf16_f32 v16, v25, v16
	v_cvt_pk_bf16_f32 v17, v24, v39
	v_cvt_pk_bf16_f32 v18, v18, v20
	v_cvt_pk_bf16_f32 v19, v22, v27
	v_mul_f32_e32 v20, v26, v23
	v_mul_f32_e32 v22, v28, v82
	v_mul_f32_e32 v21, v21, v85
	v_mfma_f32_32x32x16_bf16 v[32:47], v[32:35], v[16:19], 0
	v_cvt_pk_bf16_f32 v82, v31, v29
	v_cvt_pk_bf16_f32 v83, v84, v83
	v_cvt_pk_bf16_f32 v84, v21, v22
	v_cvt_pk_bf16_f32 v85, v20, v30
	v_mul_f32_e32 v111, v86, v87
	v_cmp_nle_f32_e32 vcc, s18, v111
	s_cmp_eq_u64 vcc, exec
	v_mfma_f32_32x32x16_bf16 v[16:31], v[56:59], v[16:19], 0
	s_cselect_b64 s[82:83], -1, 0
	s_or_b64 s[78:79], s[78:79], s[82:83]
	s_and_b64 vcc, exec, s[78:79]
	v_mfma_f32_32x32x16_bf16 v[32:47], v[48:51], v[82:85], v[32:47]
	v_mfma_f32_32x32x16_bf16 v[16:31], v[52:55], v[82:85], v[16:31]
	s_cbranch_vccnz .LBB0_297
; __device__ __forceinline__ void attnB_wave(LAS unsigned char* st, const bf16* QKV, bf16* O, float* sso, int b, int h, int qi, int lane) {
;     ...
;             ATD_VFRAGS(vfc, A, st, (i + 1) & 1);
;             if (i + 3 < n) ATD_DMA(A, st, qi - (i + 3), (i + 1) & 1);
	s_waitcnt vmcnt(8)
	ds_read_b64_tr_b16 v[82:83], v60 offset:12288
	ds_read_b64_tr_b16 v[84:85], v61 offset:12288
	ds_read_b64_tr_b16 v[88:89], v61 offset:14336
	ds_read_b64_tr_b16 v[86:87], v60 offset:14336
	ds_read_b64_tr_b16 v[90:91], v62 offset:12288
	ds_read_b64_tr_b16 v[92:93], v63 offset:12288
	ds_read_b64_tr_b16 v[96:97], v63 offset:14336
	ds_read_b64_tr_b16 v[94:95], v62 offset:14336
	s_waitcnt lgkmcnt(0)
	s_cmp_gt_u32 s81, 2
	s_mov_b64 s[78:79], -1
	s_cbranch_scc0 .LBB0_281
	s_mul_i32 s3, s81, 0x18000
	s_add_i32 s10, s3, 0xfffb8000
	s_lshl_b64 s[78:79], s[10:11], 1
	v_lshl_add_u64 v[48:49], v[102:103], 0, s[78:79]
	v_lshl_add_u64 v[50:51], v[48:49], 0, s[22:23]
	s_add_i32 m0, s33, 0x2000
	v_readlane_b32 s10, v255, 32
	global_load_lds_dwordx4 v[50:51], off
	v_lshl_add_u64 v[50:51], v[104:105], 0, s[78:79]
	v_lshl_add_u64 v[52:53], v[50:51], 0, s[74:75]
	s_mov_b32 m0, s10
	v_readlane_b32 s10, v255, 33
	global_load_lds_dwordx4 v[52:53], off
	v_lshl_add_u64 v[48:49], v[48:49], 0, s[76:77]
	s_mov_b32 m0, s10
	v_readlane_b32 s10, v255, 34
	global_load_lds_dwordx4 v[48:49], off
	v_lshl_add_u64 v[48:49], v[50:51], 0, s[24:25]
	s_mov_b32 m0, s10
	v_readlane_b32 s10, v255, 35
	global_load_lds_dwordx4 v[48:49], off
	v_lshl_add_u64 v[48:49], v[106:107], 0, s[78:79]
	s_mov_b32 m0, s10
	v_lshl_add_u64 v[50:51], v[108:109], 0, s[78:79]
	v_readlane_b32 s10, v255, 36
	global_load_lds_dwordx4 v[48:49], off
	v_lshl_add_u64 v[52:53], v[50:51], 0, s[26:27]
	s_mov_b32 m0, s10
	v_readlane_b32 s10, v255, 37
	global_load_lds_dwordx4 v[52:53], off
	v_lshl_add_u64 v[48:49], v[48:49], 0, s[28:29]
	s_mov_b32 m0, s10
	s_mov_b64 s[78:79], 0
	global_load_lds_dwordx4 v[48:49], off
	v_lshl_add_u64 v[48:49], v[50:51], 0, s[30:31]
	s_mov_b32 m0, s8
	s_nop 0
	global_load_lds_dwordx4 v[48:49], off

; __device__ __forceinline__ float ex2(float v) { return __builtin_amdgcn_exp2f(v); }
; __device__ __forceinline__ int crow(int r, int hi) { return (r & 3) + 8 * (r >> 2) + 4 * hi; }
; #define MFMA32(a, b, c) __builtin_amdgcn_mfma_f32_32x32x16_bf16((a), (b), (c), 0, 0, 0)
; template <bool diag> __device__ __forceinline__ void tileB_post(BStateL& S, const f32x16& y, const bf16x8 (&vf)[4], int ql, int hi) {
;     f32x16 bt, kk;
; #pragma unroll
;     for (int r = 0; r < 16; ++r) {
;         const float t = ex2(__builtin_amdgcn_fmed3f(y[r], -126.f, 126.f));
;         float k_ = __builtin_amdgcn_rcpf(1.0f + t);
;         float b_ = t * k_;
;         if (diag && !(crow(r, hi) < ql)) { b_ = 0.f; k_ = 1.f; }
;         bt[r] = b_; kk[r] = k_;
;     }
;     float G[4], PG[4], tot[4];
; #pragma unroll
;     for (int u = 0; u < 4; ++u) { G[u] = (kk[4 * u] * kk[4 * u + 1]) * (kk[4 * u + 2] * kk[4 * u + 3]); PG[u] = __shfl_xor(G[u], 32); tot[u] = G[u] * PG[u]; }
;     float A[4];
;     A[3] = S.C; A[2] = A[3] * tot[3]; A[1] = A[2] * tot[2]; A[0] = A[1] * tot[1];
;     const float Cn = A[0] * tot[0];
;     f32x16 w;
; #pragma unroll
;     for (int u = 0; u < 4; ++u) {
;         const float F3 = A[u] * (hi == 0 ? PG[u] : 1.0f), F2 = F3 * kk[4 * u + 3], F1 = F2 * kk[4 * u + 2], F0 = F1 * kk[4 * u + 1];
;         w[4 * u + 3] = bt[4 * u + 3] * F3; w[4 * u + 2] = bt[4 * u + 2] * F2; w[4 * u + 1] = bt[4 * u + 1] * F1; w[4 * u] = bt[4 * u] * F0;
;     }
;     S.C = Cn;
;     const bf16x8 p0 = pack8(w, 0), p1 = pack8(w, 8);
;     S.o0 = MFMA32(vf[0], p0, S.o0); S.o0 = MFMA32(vf[1], p1, S.o0);
;     S.o1 = MFMA32(vf[2], p0, S.o1); S.o1 = MFMA32(vf[3], p1, S.o1);
; __device__ __forceinline__ void attnB_wave(LAS unsigned char* st, const bf16* QKV, bf16* O, float* sso, int b, int h, int qi, int lane) {
;     ...
;         if (SB_EARLY_EXIT && __all(!(S.C >= 0x1p-126f))) break;
.LBB0_293:
	v_med3_f32 v110, v48, s9, v217
	v_exp_f32_e32 v138, v110
	v_med3_f32 v110, v49, s9, v217
	v_exp_f32_e32 v139, v110
	s_mov_b64 s[84:85], -1
	v_add_f32_e32 v110, 1.0, v138
	v_rcp_f32_e32 v140, v110
	v_med3_f32 v110, v50, s9, v217
	v_add_f32_e32 v113, 1.0, v139
	v_exp_f32_e32 v142, v110
	v_med3_f32 v110, v51, s9, v217
	v_exp_f32_e32 v143, v110
	v_rcp_f32_e32 v141, v113
	v_med3_f32 v113, v52, s9, v217
	v_exp_f32_e32 v146, v113
	v_med3_f32 v113, v53, s9, v217
	v_exp_f32_e32 v147, v113
	v_med3_f32 v113, v54, s9, v217
	v_add_f32_e32 v110, 1.0, v142
	v_exp_f32_e32 v156, v113
	v_med3_f32 v113, v55, s9, v217
	v_rcp_f32_e32 v144, v110
	v_add_f32_e32 v110, 1.0, v143
	v_exp_f32_e32 v157, v113
	v_med3_f32 v113, v56, s9, v217
	v_rcp_f32_e32 v145, v110
	v_add_f32_e32 v110, 1.0, v146
	v_exp_f32_e32 v160, v113
	v_med3_f32 v113, v57, s9, v217
	v_rcp_f32_e32 v148, v110
	v_add_f32_e32 v110, 1.0, v147
	v_exp_f32_e32 v161, v113
	v_med3_f32 v113, v58, s9, v217
	v_rcp_f32_e32 v149, v110
	v_add_f32_e32 v110, 1.0, v156
	v_exp_f32_e32 v176, v113
	v_med3_f32 v113, v59, s9, v217
	v_rcp_f32_e32 v158, v110
	v_add_f32_e32 v110, 1.0, v157
	v_exp_f32_e32 v177, v113
	v_med3_f32 v113, v60, s9, v217
	v_rcp_f32_e32 v159, v110
	v_add_f32_e32 v110, 1.0, v160
	v_exp_f32_e32 v180, v113
	v_med3_f32 v113, v61, s9, v217
	v_rcp_f32_e32 v174, v110
	v_add_f32_e32 v110, 1.0, v161
	v_exp_f32_e32 v181, v113
	v_med3_f32 v113, v63, s9, v217
	v_rcp_f32_e32 v175, v110
	v_add_f32_e32 v110, 1.0, v176
	v_exp_f32_e32 v185, v113
	v_med3_f32 v113, v62, s9, v217
	v_rcp_f32_e32 v178, v110
	v_add_f32_e32 v110, 1.0, v177
	v_exp_f32_e32 v184, v113
	v_rcp_f32_e32 v179, v110
	v_add_f32_e32 v110, 1.0, v180
	v_rcp_f32_e32 v182, v110
	v_add_f32_e32 v110, 1.0, v181
	v_rcp_f32_e32 v183, v110
	v_add_f32_e32 v110, 1.0, v185
	v_rcp_f32_e32 v187, v110
	v_add_f32_e32 v110, 1.0, v184
	v_rcp_f32_e32 v186, v110
	v_mov_b32_e32 v188, v183
	v_mov_b32_e32 v189, v187
	v_mov_b32_e32 v190, v182
	v_mov_b32_e32 v191, v186
	v_mul_f32_e32 v188, v190, v188
	v_mul_f32_e32 v189, v191, v189
	v_mov_b32_e32 v190, v175
	v_pk_mul_f32 v[188:189], v[188:189], v[188:189] op_sel:[0,1] op_sel_hi:[1,0]
	ds_bpermute_b32 v189, v112, v188
	v_mov_b32_e32 v191, v179
	v_mov_b32_e32 v192, v174
	v_mov_b32_e32 v193, v178
	v_mul_f32_e32 v190, v192, v190
	v_mul_f32_e32 v191, v193, v191
	v_mov_b32_e32 v193, v188
	v_mov_b32_e32 v192, v190
	v_mov_b32_e32 v188, v191
	s_waitcnt lgkmcnt(0)
	v_mul_f32_e32 v190, v192, v188
	v_mul_f32_e32 v191, v193, v189
	ds_bpermute_b32 v110, v112, v190
	v_mov_b32_e32 v192, v149
	v_mov_b32_e32 v193, v159
	v_mov_b32_e32 v194, v148
	v_mov_b32_e32 v195, v158
	s_waitcnt lgkmcnt(0)
	v_mul_f32_e32 v190, v190, v110
	v_mul_f32_e32 v191, v191, v111
	v_mul_f32_e32 v192, v194, v192
	v_mul_f32_e32 v193, v195, v193
	v_mov_b32_e32 v195, v190
	v_mov_b32_e32 v194, v192
	v_mov_b32_e32 v190, v193
	v_mul_f32_e32 v192, v194, v190
	v_mul_f32_e32 v193, v195, v191
	ds_bpermute_b32 v195, v112, v192
	v_mov_b32_e32 v196, v141
	v_mov_b32_e32 v197, v145
	v_mov_b32_e32 v198, v140
	v_mov_b32_e32 v199, v144
	v_mul_f32_e32 v196, v198, v196
	v_mul_f32_e32 v197, v199, v197
	v_mov_b32_e32 v199, v192
	v_mov_b32_e32 v198, v196
	v_mov_b32_e32 v194, v197
	s_waitcnt lgkmcnt(0)
	v_mul_f32_e32 v196, v198, v194
	v_mul_f32_e32 v197, v199, v195
	ds_bpermute_b32 v192, v112, v196
	v_cndmask_b32_e64 v113, 1.0, v195, s[38:39]
	v_mul_f32_e32 v138, v138, v140
	v_mul_f32_e32 v139, v139, v141
	v_mul_f32_e32 v142, v142, v144
	v_mul_f32_e32 v143, v143, v145
	v_mul_f32_e32 v156, v156, v158
	v_mul_f32_e32 v157, v157, v159
	s_waitcnt lgkmcnt(0)
	v_mul_f32_e32 v194, v196, v192
	v_mul_f32_e32 v195, v197, v193
	v_cndmask_b32_e64 v140, 1.0, v192, s[38:39]
	v_mul_f32_e32 v197, v140, v195
	v_mul_f32_e32 v196, v145, v197
	v_mul_f32_e32 v145, v144, v196
	v_mul_f32_e32 v144, v141, v145
	v_mul_f32_e32 v140, v142, v196
	v_mul_f32_e32 v141, v143, v197
	v_mul_f32_e32 v143, v113, v193
	v_mul_f32_e32 v142, v159, v143
	v_mul_f32_e32 v138, v138, v144
	v_mul_f32_e32 v139, v139, v145
	v_mul_f32_e32 v145, v158, v142
	v_mul_f32_e32 v146, v146, v148
	v_mul_f32_e32 v147, v147, v149
	v_mul_f32_e32 v144, v149, v145
	v_mul_f32_e32 v142, v156, v142
	v_mul_f32_e32 v143, v157, v143
	v_mul_f32_e32 v144, v146, v144
	v_mul_f32_e32 v145, v147, v145
	v_cvt_pk_bf16_f32 v138, v138, v139
	v_cvt_pk_bf16_f32 v139, v140, v141
	v_cvt_pk_bf16_f32 v140, v144, v145
	v_cvt_pk_bf16_f32 v141, v142, v143
	v_cndmask_b32_e64 v110, 1.0, v110, s[38:39]
	v_mul_f32_e32 v147, v110, v191
	v_mfma_f32_32x32x16_bf16 v[32:47], v[82:85], v[138:141], v[32:47]
	v_cndmask_b32_e64 v110, 1.0, v189, s[38:39]
	v_mul_f32_e32 v111, v111, v110
	v_mul_f32_e32 v146, v179, v147
	v_mul_f32_e32 v110, v187, v111
	v_mul_f32_e32 v149, v178, v146
	v_mul_f32_e32 v157, v186, v110
	v_mul_f32_e32 v184, v184, v186
	v_mul_f32_e32 v185, v185, v187
	v_mfma_f32_32x32x16_bf16 v[16:31], v[90:93], v[138:141], v[16:31]
	v_mul_f32_e64 v180, v180, v182
	v_mul_f32_e64 v181, v181, v183
	v_mul_f32_e64 v176, v176, v178
	v_mul_f32_e64 v177, v177, v179
	v_mul_f32_e64 v160, v160, v174
	v_mul_f32_e64 v161, v161, v175
	v_mul_f32_e32 v148, v175, v149
	v_mul_f32_e32 v156, v183, v157
	v_mul_f32_e32 v146, v176, v146
	v_mul_f32_e32 v147, v177, v147
	v_mul_f32_e32 v148, v160, v148
	v_mul_f32_e32 v149, v161, v149
	v_mul_f32_e32 v110, v184, v110
	v_mul_f32_e32 v111, v185, v111
	v_mul_f32_e32 v144, v180, v156
	v_mul_f32_e32 v145, v181, v157
	v_cvt_pk_bf16_f32 v142, v148, v149
	v_cvt_pk_bf16_f32 v143, v146, v147
	v_cvt_pk_bf16_f32 v144, v144, v145
	v_cvt_pk_bf16_f32 v145, v110, v111
	v_mul_f32_e32 v111, v194, v195
	v_cmp_nle_f32_e32 vcc, s18, v111
	v_mfma_f32_32x32x16_bf16 v[32:47], v[86:89], v[142:145], v[32:47]
	s_cmp_eq_u64 vcc, exec
	v_mfma_f32_32x32x16_bf16 v[16:31], v[94:97], v[142:145], v[16:31]
	s_cbranch_scc1 .LBB0_286
; __device__ __forceinline__ void attnB_wave(LAS unsigned char* st, const bf16* QKV, bf16* O, float* sso, int b, int h, int qi, int lane) {
;     ...
;             ATD_VFRAGS(vfc, A, st, (i + 1) & 1);
;             if (i + 3 < n) ATD_DMA(A, st, qi - (i + 3), (i + 1) & 1);
	s_andn2_b64 vcc, exec, s[78:79]
	s_cbranch_vccnz .LBB0_285
	s_and_b32 s78, s3, 0x2000
	s_add_i32 s78, s33, s78
	v_add_u32_e32 v48, s78, v152
	v_add_u32_e32 v49, s78, v153
	s_waitcnt vmcnt(8)
	ds_read_b64_tr_b16 v[82:83], v48 offset:4096
	ds_read_b64_tr_b16 v[84:85], v49 offset:4096
	ds_read_b64_tr_b16 v[88:89], v49 offset:6144
	ds_read_b64_tr_b16 v[86:87], v48 offset:6144
	v_add_u32_e32 v48, s78, v154
	v_add_u32_e32 v49, s78, v155
	ds_read_b64_tr_b16 v[90:91], v48 offset:4096
	ds_read_b64_tr_b16 v[92:93], v49 offset:4096
	ds_read_b64_tr_b16 v[96:97], v49 offset:6144
	ds_read_b64_tr_b16 v[94:95], v48 offset:6144
	s_waitcnt lgkmcnt(0)
	s_add_i32 s79, s82, 4
	s_cmp_gt_u32 s79, s81
	s_cbranch_scc1 .LBB0_284
	s_lshl_b64 s[82:83], s[10:11], 1
	v_lshl_add_u64 v[48:49], v[102:103], 0, s[82:83]
	s_mov_b32 m0, s78
	v_lshl_add_u64 v[50:51], v[48:49], 0, s[22:23]
	global_load_lds_dwordx4 v[50:51], off
	v_lshl_add_u64 v[50:51], v[104:105], 0, s[82:83]
	v_lshl_add_u64 v[52:53], v[50:51], 0, s[74:75]
	s_add_i32 m0, s78, 0x400
	v_lshl_add_u64 v[48:49], v[48:49], 0, s[76:77]
	global_load_lds_dwordx4 v[52:53], off
	s_add_i32 m0, s78, 0x800
	s_nop 0
	global_load_lds_dwordx4 v[48:49], off
	v_lshl_add_u64 v[48:49], v[50:51], 0, s[24:25]
	s_add_i32 m0, s78, 0xc00
	v_lshl_add_u64 v[50:51], v[108:109], 0, s[82:83]
	global_load_lds_dwordx4 v[48:49], off
	v_lshl_add_u64 v[48:49], v[106:107], 0, s[82:83]
	s_add_i32 m0, s78, 0x1000
	v_lshl_add_u64 v[52:53], v[50:51], 0, s[26:27]
	global_load_lds_dwordx4 v[48:49], off
	s_add_i32 m0, s78, 0x1400
	v_lshl_add_u64 v[48:49], v[48:49], 0, s[28:29]
	global_load_lds_dwordx4 v[52:53], off
	s_add_i32 m0, s78, 0x1800
	s_nop 0
	global_load_lds_dwordx4 v[48:49], off
	v_lshl_add_u64 v[48:49], v[50:51], 0, s[30:31]
	s_add_i32 m0, s78, 0x1c00
	s_nop 0
	global_load_lds_dwordx4 v[48:49], off
	s_branch .LBB0_284

; #define LAS __attribute__((address_space(3)))
; __device__ __forceinline__ void tileA_post(AState& S, f32x16& s, const bf16x8 (&vf)[4], const LAS float* tb2, int kbase, int q0, int ql, int hi) {
;     const bool far = tileA_far(kbase, q0);
;     if (!far) {
;         const int dq = q0 + ql - kbase - 4 * hi;
; #pragma unroll
;         for (int r = 0; r < 16; ++r) { int dist = dq - ((r & 3) + 8 * (r >> 2)); dist = dist > 128 ? 128 : dist; s[r] += tb2[dist + 128]; }
;     }
.LBB0_312:
	v_add_u32_e32 v65, s94, v126
	v_sub_u32_e32 v66, v158, v65
	v_min_i32_e32 v66, 0x80, v66
	v_lshl_add_u32 v74, v66, 2, s81
	v_xad_u32 v66, v65, -1, v158
	v_min_i32_e32 v66, 0x80, v66
	v_lshl_add_u32 v75, v66, 2, s81
	v_sub_u32_e32 v66, v159, v65
	v_min_i32_e32 v66, 0x80, v66
	v_lshl_add_u32 v76, v66, 2, s81
	v_sub_u32_e32 v66, v160, v65
	v_min_i32_e32 v66, 0x80, v66
	v_lshl_add_u32 v77, v66, 2, s81
	v_sub_u32_e32 v66, v161, v65
	v_min_i32_e32 v66, 0x80, v66
	v_lshl_add_u32 v78, v66, 2, s81
	v_sub_u32_e32 v66, v174, v65
	v_min_i32_e32 v66, 0x80, v66
	v_lshl_add_u32 v79, v66, 2, s81
	v_sub_u32_e32 v66, v175, v65
	v_min_i32_e32 v66, 0x80, v66
	v_lshl_add_u32 v80, v66, 2, s81
	v_sub_u32_e32 v66, v176, v65
	v_min_i32_e32 v66, 0x80, v66
	v_lshl_add_u32 v187, v66, 2, s81
	v_sub_u32_e32 v66, v177, v65
	v_sub_u32_e32 v67, v178, v65
	v_sub_u32_e32 v68, v179, v65
	v_sub_u32_e32 v69, v180, v65
	v_sub_u32_e32 v70, v181, v65
	v_sub_u32_e32 v71, v182, v65
	v_sub_u32_e32 v72, v183, v65
	v_min_i32_e32 v66, 0x80, v66
	v_min_i32_e32 v67, 0x80, v67
	v_min_i32_e32 v68, 0x80, v68
	v_min_i32_e32 v69, 0x80, v69
	v_min_i32_e32 v70, 0x80, v70
	v_min_i32_e32 v71, 0x80, v71
	v_min_i32_e32 v72, 0x80, v72
	v_sub_u32_e32 v65, v184, v65
	v_lshl_add_u32 v66, v66, 2, s81
	v_lshl_add_u32 v67, v67, 2, s81
	v_lshl_add_u32 v68, v68, 2, s81
	v_lshl_add_u32 v69, v69, 2, s81
	v_lshl_add_u32 v70, v70, 2, s81
	v_lshl_add_u32 v71, v71, 2, s81
	v_lshl_add_u32 v72, v72, 2, s81
	v_min_i32_e32 v65, 0x80, v65
	v_lshl_add_u32 v65, v65, 2, s81
	ds_read_b32 v66, v66 offset:512
	ds_read_b32 v67, v67 offset:512
	ds_read_b32 v68, v68 offset:512
	ds_read_b32 v69, v69 offset:512
	ds_read_b32 v70, v70 offset:512
	ds_read_b32 v71, v71 offset:512
	ds_read_b32 v72, v72 offset:512
	ds_read_b32 v73, v65 offset:512
	ds_read_b32 v74, v74 offset:512
	ds_read_b32 v75, v75 offset:512
	ds_read_b32 v76, v76 offset:512
	ds_read_b32 v77, v77 offset:512
	ds_read_b32 v78, v78 offset:512
	ds_read_b32 v79, v79 offset:512
	ds_read_b32 v186, v80 offset:512
	ds_read_b32 v187, v187 offset:512
	s_waitcnt lgkmcnt(0)
	v_add_f32_e32 v62, v62, v72
	v_add_f32_e32 v63, v63, v73
	v_add_f32_e32 v60, v60, v70
	v_add_f32_e32 v61, v61, v71
	v_add_f32_e32 v58, v58, v68
	v_add_f32_e32 v59, v59, v69
	v_add_f32_e32 v56, v56, v66
	v_add_f32_e32 v57, v57, v67
	v_add_f32_e32 v54, v54, v186
	v_add_f32_e32 v55, v55, v187
	v_add_f32_e32 v52, v52, v78
	v_add_f32_e32 v53, v53, v79
	v_add_f32_e32 v50, v50, v76
	v_add_f32_e32 v51, v51, v77
	v_add_f32_e32 v48, v48, v74
	v_add_f32_e32 v49, v49, v75
; __device__ __forceinline__ float ex2(float v) { return __builtin_amdgcn_exp2f(v); }
; #define MFMA32(a, b, c) __builtin_amdgcn_mfma_f32_32x32x16_bf16((a), (b), (c), 0, 0, 0)
; __device__ __forceinline__ void tileA_post(AState& S, f32x16& s, const bf16x8 (&vf)[4], const LAS float* tb2, int kbase, int q0, int ql, int hi) {
;     ...
;     float mx = s[0];
; #pragma unroll
;     for (int r = 1; r < 16; ++r) mx = fmaxf(mx, s[r]);
;     mx = fmaxf(mx, __shfl_xor(mx, 32));
;     const float mnew = fmaxf(S.mrun, mx), alpha = ex2(S.mrun - mnew);
;     S.mrun = mnew;
;     float rs = 0.f;
; #pragma unroll
;     for (int r = 0; r < 16; ++r) { s[r] = ex2(s[r] - mnew); rs += s[r]; }
;     S.l = S.l * alpha + rs;
; #pragma unroll
;     for (int r = 0; r < 16; ++r) { S.o0[r] *= alpha; S.o1[r] *= alpha; }
;     const bf16x8 p0 = pack8(s, 0), p1 = pack8(s, 8);
;     S.o0 = MFMA32(vf[0], p0, S.o0); S.o0 = MFMA32(vf[1], p1, S.o0);
;     S.o1 = MFMA32(vf[2], p0, S.o1); S.o1 = MFMA32(vf[3], p1, S.o1);
; __device__ __forceinline__ void attnA_wave(LAS unsigned char* st, const LAS float* tb2, const bf16* QKV, bf16* O, float* sso, int b, int h, int qblk, int lane) {
;     ...
;             ATD_VFRAGS(vfc, A, st, (i + 1) & 1);
;             if (i + 3 < n) ATD_DMA(A, st, t0 + i + 3, (i + 1) & 1);
.LBB0_313:
	s_nop 0
	v_max_f32_e32 v65, v49, v49
	v_max_f32_e32 v66, v48, v48
	v_max_f32_e32 v65, v66, v65
	v_max3_f32 v65, v65, v50, v51
	v_max3_f32 v65, v65, v52, v53
	v_max3_f32 v65, v65, v54, v55
	v_max3_f32 v65, v65, v56, v57
	v_max3_f32 v65, v65, v58, v59
	v_cmp_lt_i32_e32 vcc, v208, v207
	v_max3_f32 v65, v65, v60, v61
	v_max3_f32 v65, v65, v62, v63
	v_cndmask_b32_e32 v66, v206, v208, vcc
	v_lshlrev_b32_e32 v66, 2, v66
	ds_bpermute_b32 v66, v66, v65
	s_andn2_b64 vcc, exec, s[78:79]
	s_waitcnt lgkmcnt(0)
	v_max3_f32 v186, v64, v65, v66
	v_sub_f32_e32 v48, v48, v186
	v_sub_f32_e32 v80, v64, v186
	v_exp_f32_e32 v64, v48
	v_sub_f32_e32 v48, v49, v186
	v_exp_f32_e32 v65, v48
	v_sub_f32_e32 v48, v50, v186
	v_exp_f32_e32 v66, v48
	v_sub_f32_e32 v48, v51, v186
	v_exp_f32_e32 v67, v48
	v_sub_f32_e32 v48, v52, v186
	v_exp_f32_e32 v68, v48
	v_sub_f32_e32 v48, v53, v186
	v_exp_f32_e32 v69, v48
	v_sub_f32_e32 v48, v54, v186
	v_exp_f32_e32 v70, v48
	v_sub_f32_e32 v48, v55, v186
	v_exp_f32_e32 v71, v48
	v_sub_f32_e32 v48, v56, v186
	v_exp_f32_e32 v72, v48
	v_sub_f32_e32 v48, v57, v186
	v_exp_f32_e32 v73, v48
	v_sub_f32_e32 v48, v58, v186
	v_exp_f32_e32 v74, v48
	v_sub_f32_e32 v48, v59, v186
	v_exp_f32_e32 v75, v48
	v_sub_f32_e32 v48, v60, v186
	v_exp_f32_e32 v80, v80
	v_exp_f32_e32 v76, v48
	v_sub_f32_e32 v48, v61, v186
	v_exp_f32_e32 v77, v48
	v_sub_f32_e32 v48, v62, v186
	v_exp_f32_e32 v78, v48
	v_sub_f32_e32 v48, v63, v186
	v_exp_f32_e32 v79, v48
	v_mul_f32_e32 v14, v14, v80
	v_mul_f32_e32 v15, v15, v80
	v_mul_f32_e32 v12, v12, v80
	v_mul_f32_e32 v13, v13, v80
	v_mul_f32_e32 v10, v10, v80
	v_mul_f32_e32 v11, v11, v80
	v_mul_f32_e32 v8, v8, v80
	v_mul_f32_e32 v9, v9, v80
	v_mul_f32_e32 v6, v6, v80
	v_mul_f32_e32 v7, v7, v80
	v_mul_f32_e32 v4, v4, v80
	v_mul_f32_e32 v5, v5, v80
	v_mul_f32_e32 v2, v2, v80
	v_mul_f32_e32 v3, v3, v80
	v_mul_f32_e32 v0, v0, v80
	v_mul_f32_e32 v1, v1, v80
	v_mul_f32_e32 v30, v30, v80
	v_mul_f32_e32 v31, v31, v80
	v_mul_f32_e32 v28, v28, v80
	v_mul_f32_e32 v29, v29, v80
	v_mul_f32_e32 v26, v26, v80
	v_mul_f32_e32 v27, v27, v80
	v_mul_f32_e32 v24, v24, v80
	v_mul_f32_e32 v25, v25, v80
	v_mul_f32_e32 v22, v22, v80
	v_mul_f32_e32 v23, v23, v80
	v_mul_f32_e32 v20, v20, v80
	v_mul_f32_e32 v21, v21, v80
	v_mul_f32_e32 v18, v18, v80
	v_mul_f32_e32 v19, v19, v80
	v_mul_f32_e32 v16, v16, v80
	v_mul_f32_e32 v17, v17, v80
	v_cvt_pk_bf16_f32 v48, v64, v65
	v_cvt_pk_bf16_f32 v49, v66, v67
	v_cvt_pk_bf16_f32 v50, v68, v69
	v_cvt_pk_bf16_f32 v51, v70, v71
	v_cvt_pk_bf16_f32 v52, v72, v73
	v_cvt_pk_bf16_f32 v53, v74, v75
	v_mfma_f32_32x32x16_bf16 v[0:15], v[98:101], v[48:51], v[0:15]
	v_cvt_pk_bf16_f32 v54, v76, v77
	v_cvt_pk_bf16_f32 v55, v78, v79
	v_mfma_f32_32x32x16_bf16 v[16:31], v[106:109], v[48:51], v[16:31]
	s_nop 0
	v_mfma_f32_32x32x16_bf16 v[0:15], v[102:105], v[52:55], v[0:15]
	v_mfma_f32_32x32x16_bf16 v[16:31], v[110:113], v[52:55], v[16:31]
	s_cbranch_vccnz .LBB0_323
	s_and_b32 s78, s90, 0x2000
	s_add_i32 s78, s33, s78
	v_add_u32_e32 v48, s78, v152
	v_add_u32_e32 v49, s78, v153
	s_waitcnt vmcnt(8)
	ds_read_b64_tr_b16 v[98:99], v48 offset:4096
	ds_read_b64_tr_b16 v[100:101], v49 offset:4096
	ds_read_b64_tr_b16 v[104:105], v49 offset:6144
	ds_read_b64_tr_b16 v[102:103], v48 offset:6144
	v_add_u32_e32 v48, s78, v154
	v_add_u32_e32 v49, s78, v155
	ds_read_b64_tr_b16 v[106:107], v48 offset:4096
	ds_read_b64_tr_b16 v[108:109], v49 offset:4096
	ds_read_b64_tr_b16 v[112:113], v49 offset:6144
	ds_read_b64_tr_b16 v[110:111], v48 offset:6144
	s_waitcnt lgkmcnt(0)
	s_cmp_ge_i32 s3, s88
	s_cbranch_scc1 .LBB0_316
	s_addk_i32 s94, 0x60
	v_mad_i64_i32 v[48:49], s[84:85], s94, v218, v[142:143]
	s_mov_b32 m0, s78
	v_lshl_add_u64 v[50:51], v[48:49], 0, s[34:35]
	global_load_lds_dwordx4 v[50:51], off
	v_mad_i64_i32 v[50:51], s[84:85], s94, v218, v[144:145]
	v_lshl_add_u64 v[52:53], v[50:51], 0, s[96:97]
	s_add_i32 m0, s78, 0x400
	v_lshl_add_u64 v[48:49], v[48:49], 0, s[72:73]
	global_load_lds_dwordx4 v[52:53], off
	s_add_i32 m0, s78, 0x800
	s_nop 0
	global_load_lds_dwordx4 v[48:49], off
	v_lshl_add_u64 v[48:49], v[50:51], 0, s[6:7]
	s_add_i32 m0, s78, 0xc00
	v_mad_i64_i32 v[50:51], s[84:85], s94, v218, v[148:149]
	global_load_lds_dwordx4 v[48:49], off
	v_mad_i64_i32 v[48:49], s[84:85], s94, v218, v[146:147]
	s_add_i32 m0, s78, 0x1000
	v_lshl_add_u64 v[52:53], v[50:51], 0, s[26:27]
	global_load_lds_dwordx4 v[48:49], off
	s_add_i32 m0, s78, 0x1400
	v_lshl_add_u64 v[48:49], v[48:49], 0, s[28:29]
	global_load_lds_dwordx4 v[52:53], off
	s_add_i32 m0, s78, 0x1800
	s_nop 0
	global_load_lds_dwordx4 v[48:49], off
	v_lshl_add_u64 v[48:49], v[50:51], 0, s[30:31]
	s_add_i32 m0, s78, 0x1c00
	s_nop 0
	global_load_lds_dwordx4 v[48:49], off

; __device__ __forceinline__ unsigned pk2(float lo, float hi) { return pg8::cvt_pk_bf16(lo, hi); }
; __device__ __forceinline__ void store_o(bf16* Op, const f32x16& o0, const f32x16& o1, float inv, int hi, float* ssrow) {
;     float p = 0.f;
; #pragma unroll
;     for (int u = 0; u < 4; ++u) {
;         const f32x4 a = (f32x4){o0[4 * u] * inv, o0[4 * u + 1] * inv, o0[4 * u + 2] * inv, o0[4 * u + 3] * inv}, c = (f32x4){o1[4 * u] * inv, o1[4 * u + 1] * inv, o1[4 * u + 2] * inv, o1[4 * u + 3] * inv};
;         p += ((a.x * a.x + a.y * a.y) + (a.z * a.z + a.w * a.w)) + ((c.x * c.x + c.y * c.y) + (c.z * c.z + c.w * c.w));
;         u32x2 w; w.x = pk2(a.x, a.y); w.y = pk2(a.z, a.w);
;         *(u32x2*)(Op + 8 * u + 4 * hi) = w;
;         u32x2 w1; w1.x = pk2(c.x, c.y); w1.y = pk2(c.z, c.w);
;         *(u32x2*)(Op + 32 + 8 * u + 4 * hi) = w1;
;     }
;     p += __shfl_xor(p, 32);
;     if (hi == 0) atomicAdd(ssrow, p);
; }
; __device__ __forceinline__ void attnA_wave(LAS unsigned char* st, const LAS float* tb2, const bf16* QKV, bf16* O, float* sso, int b, int h, int qblk, int lane) {
;     ...
;     asm volatile("s_waitcnt vmcnt(0) lgkmcnt(0)" ::: "memory");
;     S.l += __shfl_xor(S.l, 32);
;     store_o(O + (tb + q0 + ql) * 1024 + h * 64, S.o0, S.o1, 1.0f / S.l, hi, sso + tb + q0 + ql);
.LBB0_327:
	s_lshl_b32 s3, s80, 6
	s_mov_b32 s86, 0x3fb8aa3b
	v_cmp_lt_i32_e32 vcc, v208, v207
	v_lshlrev_b32_e32 v80, 11, v156
	s_lshl_b32 s10, s3, 1
	v_cndmask_b32_e32 v32, v206, v208, vcc
	v_lshlrev_b32_e32 v35, 2, v32
	ds_bpermute_b32 v32, v35, v65
	s_waitcnt vmcnt(0) lgkmcnt(0)
	s_waitcnt lgkmcnt(0)
	v_add_f32_e32 v34, v65, v32
	v_div_scale_f32 v36, s[12:13], v34, v34, 1.0
	v_rcp_f32_e32 v37, v36
	v_lshl_add_u64 v[32:33], s[4:5], 0, v[80:81]
	v_lshl_add_u64 v[32:33], v[32:33], 0, s[10:11]
	v_lshl_add_u64 v[32:33], v[126:127], 1, v[32:33]
	v_fma_f32 v38, -v36, v37, 1.0
	v_fmac_f32_e32 v37, v38, v37
	v_div_scale_f32 v38, vcc, 1.0, v34, 1.0
	v_mul_f32_e32 v39, v38, v37
	v_fma_f32 v40, -v36, v39, v38
	v_fmac_f32_e32 v39, v40, v37
	v_fma_f32 v36, -v36, v39, v38
	v_div_fmas_f32 v36, v36, v37, v39
	v_div_fixup_f32 v34, v36, v34, 1.0
	v_mul_f32_e32 v0, v0, v34
	v_mul_f32_e32 v1, v1, v34
	v_mul_f32_e32 v2, v2, v34
	v_mul_f32_e32 v3, v3, v34
	v_mul_f32_e32 v16, v16, v34
	v_mul_f32_e32 v17, v17, v34
	v_mul_f32_e32 v18, v18, v34
	v_mul_f32_e32 v19, v19, v34
	v_mul_f32_e32 v36, v0, v0
	v_mul_f32_e32 v37, v1, v1
	v_cvt_pk_bf16_f32 v0, v0, v1
	v_cvt_pk_bf16_f32 v1, v2, v3
	flat_store_dwordx2 v[32:33], v[0:1]
	v_cvt_pk_bf16_f32 v0, v16, v17
	v_cvt_pk_bf16_f32 v1, v18, v19
	v_mul_f32_e32 v38, v2, v2
	v_mul_f32_e32 v39, v3, v3
	flat_store_dwordx2 v[32:33], v[0:1] offset:64
	v_mul_f32_e32 v0, v4, v34
	v_mul_f32_e32 v1, v5, v34
	v_mul_f32_e32 v2, v6, v34
	v_mul_f32_e32 v3, v7, v34
	v_mul_f32_e32 v40, v16, v16
	v_mul_f32_e32 v41, v17, v17
	v_mul_f32_e32 v42, v18, v18
	v_mul_f32_e32 v43, v19, v19
	v_mul_f32_e32 v4, v20, v34
	v_mul_f32_e32 v5, v21, v34
	v_mul_f32_e32 v6, v22, v34
	v_mul_f32_e32 v7, v23, v34
	v_mul_f32_e32 v16, v0, v0
	v_mul_f32_e32 v17, v1, v1
	v_mul_f32_e32 v18, v2, v2
	v_mul_f32_e32 v19, v3, v3
	v_cvt_pk_bf16_f32 v0, v0, v1
	v_cvt_pk_bf16_f32 v1, v2, v3
	flat_store_dwordx2 v[32:33], v[0:1] offset:16
	v_cvt_pk_bf16_f32 v0, v4, v5
	v_cvt_pk_bf16_f32 v1, v6, v7
	v_add_f32_e32 v18, v18, v19
	v_add_f32_e32 v16, v16, v17
	v_mul_f32_e32 v20, v4, v4
	v_mul_f32_e32 v21, v5, v5
	v_mul_f32_e32 v22, v6, v6
	v_mul_f32_e32 v23, v7, v7
	flat_store_dwordx2 v[32:33], v[0:1] offset:80
	v_mul_f32_e32 v0, v8, v34
	v_mul_f32_e32 v1, v9, v34
	v_mul_f32_e32 v2, v10, v34
	v_mul_f32_e32 v3, v11, v34
	v_add_f32_e32 v16, v16, v18
	v_add_f32_e32 v17, v42, v43
	v_add_f32_e32 v18, v40, v41
	v_mul_f32_e32 v6, v26, v34
	v_mul_f32_e32 v7, v27, v34
	v_mul_f32_e32 v8, v0, v0
	v_mul_f32_e32 v9, v1, v1
	v_cvt_pk_bf16_f32 v0, v0, v1
	v_cvt_pk_bf16_f32 v1, v2, v3
	v_add_f32_e32 v22, v22, v23
	v_add_f32_e32 v20, v20, v21
	v_add_f32_e32 v17, v18, v17
	v_add_f32_e32 v18, v38, v39
	v_add_f32_e32 v19, v36, v37
	v_mul_f32_e32 v4, v24, v34
	v_mul_f32_e32 v5, v25, v34
	v_mul_f32_e32 v10, v2, v2
	v_mul_f32_e32 v11, v3, v3
	v_mul_f32_e32 v26, v6, v6
	v_mul_f32_e32 v27, v7, v7
	flat_store_dwordx2 v[32:33], v[0:1] offset:32
	v_cvt_pk_bf16_f32 v1, v6, v7
	v_mul_f32_e32 v2, v12, v34
	v_mul_f32_e32 v3, v13, v34
	v_mul_f32_e32 v6, v28, v34
	v_mul_f32_e32 v7, v29, v34
	v_mul_f32_e32 v12, v30, v34
	v_mul_f32_e32 v13, v31, v34
	v_add_f32_e32 v20, v20, v22
	v_add_f32_e32 v18, v19, v18
	v_mul_f32_e32 v24, v4, v4
	v_mul_f32_e32 v25, v5, v5
	v_cvt_pk_bf16_f32 v0, v4, v5
	v_mul_f32_e32 v4, v14, v34
	v_mul_f32_e32 v5, v15, v34
	v_mul_f32_e32 v28, v6, v6
	v_mul_f32_e32 v29, v7, v7
	v_mul_f32_e32 v30, v12, v12
	v_mul_f32_e32 v31, v13, v13
	v_add_f32_e32 v16, v16, v20
	v_add_f32_e32 v17, v18, v17
	v_add_f32_e32 v10, v10, v11
	v_add_f32_e32 v8, v8, v9
	flat_store_dwordx2 v[32:33], v[0:1] offset:96
	v_mul_f32_e32 v0, v2, v2
	v_mul_f32_e32 v1, v3, v3
	v_mul_f32_e32 v14, v4, v4
	v_mul_f32_e32 v15, v5, v5
	v_add_f32_e32 v16, v17, v16
	v_add_f32_e32 v17, v26, v27
	v_add_f32_e32 v18, v24, v25
	v_add_f32_e32 v8, v8, v10
	v_add_f32_e32 v9, v30, v31
	v_add_f32_e32 v10, v28, v29
	v_add_f32_e32 v17, v18, v17
	v_add_f32_e32 v9, v10, v9
	v_add_f32_e32 v10, v14, v15
	v_add_f32_e32 v0, v0, v1
	v_add_f32_e32 v8, v8, v17
	v_add_f32_e32 v0, v0, v10
	v_add_f32_e32 v8, v8, v16
	v_add_f32_e32 v0, v0, v9
	v_add_f32_e32 v0, v0, v8
	ds_bpermute_b32 v1, v35, v0
	v_cvt_pk_bf16_f32 v2, v2, v3
	v_cvt_pk_bf16_f32 v3, v4, v5
	flat_store_dwordx2 v[32:33], v[2:3] offset:48
	v_cvt_pk_bf16_f32 v2, v6, v7
	v_cvt_pk_bf16_f32 v3, v12, v13
	flat_store_dwordx2 v[32:33], v[2:3] offset:112
	s_and_saveexec_b64 s[12:13], s[38:39]
	s_xor_b64 s[12:13], exec, s[12:13]
	s_cbranch_execz .LBB0_300
	s_lshl_b32 s10, s2, 2
	s_waitcnt lgkmcnt(0)
	v_add_f32_e32 v2, v0, v1
	v_lshl_add_u64 v[0:1], v[140:141], 0, s[10:11]
	flat_atomic_add_f32 v[0:1], v2
	s_branch .LBB0_300
